# GDN scan: post-barrier LDS reads issued ahead of the next chunk's image copy
# speedup vs baseline: 1.0026x; 1.0026x over previous
.LBB0_708:
	s_waitcnt vmcnt(1)
	v_lshlrev_b32_e32 v92, 16, v76
	v_and_b32_e32 v93, 0xffff0000, v76
	v_mul_f32_e32 v76, 0xbfb8aa3b, v92
	v_exp_f32_e32 v76, v76
	s_waitcnt lgkmcnt(15)
	v_add_f32_e32 v182, 0, v174
	v_add_f32_e32 v183, v182, v175
	v_add_f32_e32 v76, 1.0, v76
	v_rcp_f32_e32 v94, v76
	v_mul_f32_e32 v76, 0xbfb8aa3b, v93
	v_exp_f32_e32 v76, v76
	s_waitcnt lgkmcnt(14)
	v_add_f32_e32 v182, v183, v176
	v_add_f32_e32 v183, v182, v177
	v_add_f32_e32 v76, 1.0, v76
	v_rcp_f32_e32 v95, v76
	s_mov_b32 s8, 0xd000000
	s_add_u32 s17, s17, 4
	s_waitcnt lgkmcnt(13)
	v_add_f32_e32 v182, v183, v178
	v_add_f32_e32 v183, v182, v179
	v_pk_mul_f32 v[92:93], v[94:95], v[92:93]
	s_addc_u32 s18, s18, 0
	s_add_i32 s0, s0, -1
	v_lshl_add_u64 v[122:123], v[122:123], 0, s[6:7]
	s_waitcnt lgkmcnt(12)
	v_add_f32_e32 v182, v183, v180
	v_add_f32_e32 v182, v182, v181
	v_fmamk_f32 v182, v182, 0x3c000000, v162
	v_rsq_f32_e32 v88, v182
	v_lshl_add_u64 v[126:127], v[126:127], 0, s[6:7]
	s_cmp_lg_u32 s0, 0
	s_waitcnt lgkmcnt(11)
	v_and_b32_e32 v91, 0xffff0000, v84
	v_lshlrev_b32_e32 v90, 16, v84
	v_pk_mul_f32 v[90:91], v[88:89], v[90:91] op_sel_hi:[0,1]
	v_pk_mul_f32 v[90:91], v[92:93], v[90:91]
	v_and_b32_e32 v93, 0xffff0000, v85
	v_lshlrev_b32_e32 v92, 16, v85
	v_and_b32_e32 v85, 0xffff0000, v77
	v_lshlrev_b32_e32 v84, 16, v77
	v_mul_f32_e32 v76, 0xbfb8aa3b, v84
	v_mul_f32_e32 v77, 0xbfb8aa3b, v85
	v_exp_f32_e32 v76, v76
	v_exp_f32_e32 v77, v77
	v_pk_mul_f32 v[92:93], v[88:89], v[92:93] op_sel_hi:[0,1]
	v_add_f32_e32 v76, 1.0, v76
	v_add_f32_e32 v77, 1.0, v77
	v_rcp_f32_e32 v76, v76
	v_rcp_f32_e32 v77, v77
	s_nop 0
	v_pk_mul_f32 v[76:77], v[76:77], v[84:85]
	s_nop 0
	v_pk_mul_f32 v[84:85], v[76:77], v[92:93]
	v_lshlrev_b32_e32 v92, 16, v78
	v_and_b32_e32 v93, 0xffff0000, v78
	v_mul_f32_e32 v78, 0xbfb8aa3b, v92
	v_exp_f32_e32 v78, v78
	v_and_b32_e32 v77, 0xffff0000, v86
	v_lshlrev_b32_e32 v76, 16, v86
	v_pk_mul_f32 v[76:77], v[88:89], v[76:77] op_sel_hi:[0,1]
	v_add_f32_e32 v78, 1.0, v78
	v_rcp_f32_e32 v94, v78
	v_mul_f32_e32 v78, 0xbfb8aa3b, v93
	v_exp_f32_e32 v78, v78
	v_lshlrev_b32_e32 v86, 16, v79
	v_add_f32_e32 v78, 1.0, v78
	v_rcp_f32_e32 v95, v78
	v_mul_f32_e32 v78, 0xbfb8aa3b, v86
	v_exp_f32_e32 v78, v78
	v_pk_mul_f32 v[92:93], v[94:95], v[92:93]
	s_nop 0
	v_pk_mul_f32 v[92:93], v[92:93], v[76:77]
	v_and_b32_e32 v77, 0xffff0000, v87
	v_lshlrev_b32_e32 v76, 16, v87
	v_and_b32_e32 v87, 0xffff0000, v79
	v_mul_f32_e32 v79, 0xbfb8aa3b, v87
	v_exp_f32_e32 v79, v79
	v_add_f32_e32 v78, 1.0, v78
	v_rcp_f32_e32 v78, v78
	v_pk_mul_f32 v[76:77], v[88:89], v[76:77] op_sel_hi:[0,1]
	v_add_f32_e32 v79, 1.0, v79
	v_rcp_f32_e32 v79, v79
	s_nop 0
	v_pk_mul_f32 v[78:79], v[78:79], v[86:87]
	s_nop 0
	v_pk_mul_f32 v[86:87], v[78:79], v[76:77]
	v_cvt_pk_bf16_f32 v76, v90, v91
	v_cvt_pk_bf16_f32 v79, v86, v87
	s_waitcnt vmcnt(0)
	v_lshlrev_b32_e32 v86, 16, v72
	v_and_b32_e32 v87, 0xffff0000, v72
	v_mul_f32_e32 v72, 0xbfb8aa3b, v86
	v_exp_f32_e32 v72, v72
	v_cvt_pk_bf16_f32 v77, v84, v85
	s_waitcnt lgkmcnt(10)
	v_and_b32_e32 v85, 0xffff0000, v80
	v_lshlrev_b32_e32 v84, 16, v80
	v_add_f32_e32 v72, 1.0, v72
	v_rcp_f32_e32 v90, v72
	v_mul_f32_e32 v72, 0xbfb8aa3b, v87
	v_exp_f32_e32 v72, v72
	v_pk_mul_f32 v[84:85], v[88:89], v[84:85] op_sel_hi:[0,1]
	v_lshlrev_b32_e32 v80, 16, v73
	v_cvt_pk_bf16_f32 v78, v92, v93
	v_add_f32_e32 v72, 1.0, v72
	v_rcp_f32_e32 v91, v72
	v_mul_f32_e32 v72, 0xbfb8aa3b, v80
	v_exp_f32_e32 v72, v72
	v_pk_mul_f32 v[86:87], v[90:91], v[86:87]
	s_nop 0
	v_pk_mul_f32 v[84:85], v[86:87], v[84:85]
	v_and_b32_e32 v87, 0xffff0000, v81
	v_lshlrev_b32_e32 v86, 16, v81
	v_and_b32_e32 v81, 0xffff0000, v73
	v_mul_f32_e32 v73, 0xbfb8aa3b, v81
	v_exp_f32_e32 v73, v73
	v_add_f32_e32 v72, 1.0, v72
	v_rcp_f32_e32 v72, v72
	v_pk_mul_f32 v[86:87], v[88:89], v[86:87] op_sel_hi:[0,1]
	v_add_f32_e32 v73, 1.0, v73
	v_rcp_f32_e32 v73, v73
	s_nop 0
	v_pk_mul_f32 v[72:73], v[72:73], v[80:81]
	s_nop 0
	v_pk_mul_f32 v[80:81], v[72:73], v[86:87]
	v_lshlrev_b32_e32 v86, 16, v74
	v_and_b32_e32 v87, 0xffff0000, v74
	v_mul_f32_e32 v74, 0xbfb8aa3b, v86
	v_exp_f32_e32 v74, v74
	v_and_b32_e32 v73, 0xffff0000, v82
	v_lshlrev_b32_e32 v72, 16, v82
	v_pk_mul_f32 v[72:73], v[88:89], v[72:73] op_sel_hi:[0,1]
	v_add_f32_e32 v74, 1.0, v74
	v_rcp_f32_e32 v90, v74
	v_mul_f32_e32 v74, 0xbfb8aa3b, v87
	v_exp_f32_e32 v74, v74
	v_lshlrev_b32_e32 v82, 16, v75
	v_add_f32_e32 v74, 1.0, v74
	v_rcp_f32_e32 v91, v74
	v_mul_f32_e32 v74, 0xbfb8aa3b, v82
	v_exp_f32_e32 v74, v74
	v_pk_mul_f32 v[86:87], v[90:91], v[86:87]
	s_nop 0
	v_pk_mul_f32 v[86:87], v[86:87], v[72:73]
	v_and_b32_e32 v73, 0xffff0000, v83
	v_lshlrev_b32_e32 v72, 16, v83
	v_and_b32_e32 v83, 0xffff0000, v75
	v_mul_f32_e32 v75, 0xbfb8aa3b, v83
	v_exp_f32_e32 v75, v75
	v_add_f32_e32 v74, 1.0, v74
	v_rcp_f32_e32 v74, v74
	v_pk_mul_f32 v[72:73], v[88:89], v[72:73] op_sel_hi:[0,1]
	v_add_f32_e32 v75, 1.0, v75
	v_rcp_f32_e32 v75, v75
	s_nop 0
	v_pk_mul_f32 v[74:75], v[74:75], v[82:83]
	s_nop 0
	v_pk_mul_f32 v[82:83], v[74:75], v[72:73]
	v_cvt_pk_bf16_f32 v73, v80, v81
	v_lshl_add_u64 v[80:81], s[92:93], 0, v[120:121]
	v_add_co_u32_e32 v80, vcc, s8, v80
	s_mov_b64 s[8:9], 0x20000
	v_lshl_add_u64 v[120:121], v[120:121], 0, s[8:9]
	s_mov_b64 s[8:9], 0x4000
	v_addc_co_u32_e32 v81, vcc, 0, v81, vcc
	v_lshl_add_u64 v[124:125], v[124:125], 0, s[8:9]
	v_cvt_pk_bf16_f32 v72, v84, v85
	v_cvt_pk_bf16_f32 v74, v86, v87
	v_cvt_pk_bf16_f32 v75, v82, v83
	global_store_dwordx4 v[80:81], v[76:79], off offset:1024
	global_store_dwordx4 v[80:81], v[72:75], off offset:1040
	s_barrier
	s_cbranch_scc0 .LBB0_706

.LBB0_711:
	v_add_co_u32_e32 v72, vcc, 0x2001000, v72
	v_cvt_pk_bf16_f32 v92, v52, v53
	s_nop 0
	v_addc_co_u32_e32 v73, vcc, 0, v73, vcc
	global_load_dwordx4 v[76:79], v[72:73], off offset:128
	s_nop 0
	global_load_dwordx4 v[72:75], v[72:73], off offset:144
	v_cvt_pk_bf16_f32 v93, v54, v55
	v_cvt_pk_bf16_f32 v94, v48, v49
	v_cvt_pk_bf16_f32 v95, v50, v51
	v_cvt_pk_bf16_f32 v88, v44, v45
	v_cvt_pk_bf16_f32 v89, v46, v47
	v_cvt_pk_bf16_f32 v90, v40, v41
	v_cvt_pk_bf16_f32 v91, v42, v43
	v_cvt_pk_bf16_f32 v84, v60, v61
	v_cvt_pk_bf16_f32 v85, v62, v63
	v_cvt_pk_bf16_f32 v86, v56, v57
	v_cvt_pk_bf16_f32 v87, v58, v59
	v_cvt_pk_bf16_f32 v80, v64, v65
	v_cvt_pk_bf16_f32 v81, v66, v67
	v_cvt_pk_bf16_f32 v82, v68, v69
	v_cvt_pk_bf16_f32 v83, v70, v71
	s_waitcnt lgkmcnt(0)
	v_lshlrev_b32_e32 v238, 16, v238
	v_lshlrev_b32_e32 v239, 16, v239
	v_lshlrev_b32_e32 v240, 16, v240
	v_lshlrev_b32_e32 v241, 16, v241
	v_lshlrev_b32_e32 v242, 16, v242
	v_lshlrev_b32_e32 v243, 16, v243
	v_lshlrev_b32_e32 v244, 16, v244
	v_lshlrev_b32_e32 v245, 16, v245
	v_lshlrev_b32_e32 v246, 16, v246
	v_lshlrev_b32_e32 v247, 16, v247
	v_lshlrev_b32_e32 v248, 16, v248
	v_lshlrev_b32_e32 v249, 16, v249
	v_lshlrev_b32_e32 v250, 16, v250
	v_lshlrev_b32_e32 v251, 16, v251
	v_lshlrev_b32_e32 v252, 16, v252
	v_lshlrev_b32_e32 v253, 16, v253
	v_mfma_f32_16x16x32_bf16 v[128:131], v[128:131], v[92:95], v[238:241]
	v_mfma_f32_16x16x32_bf16 v[178:181], v[178:181], v[92:95], v[242:245]
	v_mfma_f32_16x16x32_bf16 v[186:189], v[186:189], v[92:95], v[246:249]
	v_mfma_f32_16x16x32_bf16 v[194:197], v[194:197], v[92:95], v[250:253]
	v_mfma_f32_16x16x32_bf16 v[128:131], v[174:177], v[88:91], v[128:131]
	v_mfma_f32_16x16x32_bf16 v[174:177], v[182:185], v[88:91], v[178:181]
	v_mfma_f32_16x16x32_bf16 v[178:181], v[190:193], v[88:91], v[186:189]
	v_mfma_f32_16x16x32_bf16 v[182:185], v[202:205], v[88:91], v[194:197]
	s_nop 2
	ds_read_b128 v[186:189], v161
	ds_read_b128 v[190:193], v161 offset:64
	ds_read_b128 v[194:197], v161 offset:4608
	ds_read_b128 v[202:205], v161 offset:4672
	ds_read_b128 v[238:241], v161 offset:9216
	ds_read_b128 v[242:245], v161 offset:9280
	ds_read_b128 v[246:249], v161 offset:13824
	ds_read_b128 v[250:253], v161 offset:13888
	v_mfma_f32_16x16x32_bf16 v[128:131], v[206:209], v[84:87], v[128:131]
	v_mfma_f32_16x16x32_bf16 v[174:177], v[214:217], v[84:87], v[174:177]
	v_mfma_f32_16x16x32_bf16 v[178:181], v[222:225], v[84:87], v[178:181]
	v_mfma_f32_16x16x32_bf16 v[182:185], v[230:233], v[84:87], v[182:185]
	v_mfma_f32_16x16x32_bf16 v[128:131], v[210:213], v[80:83], v[128:131]
	v_mfma_f32_16x16x32_bf16 v[174:177], v[218:221], v[80:83], v[174:177]
	v_mfma_f32_16x16x32_bf16 v[178:181], v[226:229], v[80:83], v[178:181]
	v_mfma_f32_16x16x32_bf16 v[182:185], v[234:237], v[80:83], v[182:185]
	ds_read_b128 v[206:209], v161 offset:128
	ds_read_b128 v[210:213], v161 offset:192
	ds_read_b128 v[214:217], v161 offset:4736
	ds_read_b128 v[218:221], v161 offset:4800
	ds_read_b128 v[222:225], v161 offset:9344
	ds_read_b128 v[226:229], v161 offset:9408
	ds_read_b128 v[230:233], v161 offset:13952
	ds_read_b128 v[234:237], v161 offset:14016
	v_cvt_pk_bf16_f32 v128, v128, v129
	v_cvt_pk_bf16_f32 v129, v130, v131
	v_cvt_pk_bf16_f32 v130, v174, v175
	v_cvt_pk_bf16_f32 v131, v176, v177
	v_cvt_pk_bf16_f32 v174, v178, v179
	v_cvt_pk_bf16_f32 v175, v180, v181
	v_cvt_pk_bf16_f32 v176, v182, v183
	v_cvt_pk_bf16_f32 v177, v184, v185
	s_waitcnt lgkmcnt(14)
	v_mfma_f32_16x16x32_bf16 v[178:181], v[186:189], v[92:95], 0
	s_waitcnt lgkmcnt(13)
	v_mfma_f32_16x16x32_bf16 v[182:185], v[194:197], v[92:95], 0
	s_waitcnt lgkmcnt(11)
	v_mfma_f32_16x16x32_bf16 v[186:189], v[238:241], v[92:95], 0
	s_waitcnt lgkmcnt(9)
	v_mfma_f32_16x16x32_bf16 v[92:95], v[246:249], v[92:95], 0
	v_mfma_f32_16x16x32_bf16 v[178:181], v[190:193], v[88:91], v[178:181]
	v_mfma_f32_16x16x32_bf16 v[182:185], v[202:205], v[88:91], v[182:185]
	v_mfma_f32_16x16x32_bf16 v[186:189], v[242:245], v[88:91], v[186:189]
	s_waitcnt lgkmcnt(8)
	v_mfma_f32_16x16x32_bf16 v[88:91], v[250:253], v[88:91], v[92:95]
	s_nop 2
	ds_read_b128 v[92:95], v132
	ds_read_b128 v[190:193], v138
	ds_read_b128 v[194:197], v139
	ds_read_b128 v[202:205], v140
	ds_read_b128 v[238:241], v141
	ds_read_b128 v[242:245], v142
	ds_read_b128 v[246:249], v143
	ds_read_b128 v[250:253], v144
	s_waitcnt lgkmcnt(14)
	v_mfma_f32_16x16x32_bf16 v[178:181], v[206:209], v[84:87], v[178:181]
	s_waitcnt lgkmcnt(13)
	v_mfma_f32_16x16x32_bf16 v[182:185], v[214:217], v[84:87], v[182:185]
	s_waitcnt lgkmcnt(11)
	v_mfma_f32_16x16x32_bf16 v[186:189], v[222:225], v[84:87], v[186:189]
	s_waitcnt lgkmcnt(9)
	v_mfma_f32_16x16x32_bf16 v[84:87], v[230:233], v[84:87], v[88:91]
	v_mfma_f32_16x16x32_bf16 v[88:91], v[210:213], v[80:83], v[178:181]
	v_mfma_f32_16x16x32_bf16 v[178:181], v[218:221], v[80:83], v[182:185]
	s_nop 2
	ds_read_b128 v[182:185], v133
	ds_read_b128 v[206:209], v145
	ds_read_b128 v[210:213], v146
	ds_read_b128 v[214:217], v147
	v_mfma_f32_16x16x32_bf16 v[186:189], v[226:229], v[80:83], v[186:189]
	ds_read_b128 v[218:221], v148
	ds_read_b128 v[222:225], v149
	ds_read_b128 v[226:229], v150
	ds_read_b128 v[230:233], v151
	s_waitcnt lgkmcnt(14)
	v_mfma_f32_16x16x32_bf16 v[80:83], v[234:237], v[80:83], v[84:87]
	v_mfma_f32_16x16x32_bf16 v[84:87], v[92:95], v[128:131], 0
	s_waitcnt lgkmcnt(13)
	v_mfma_f32_16x16x32_bf16 v[92:95], v[194:197], v[128:131], 0
	s_waitcnt lgkmcnt(11)
	v_mfma_f32_16x16x32_bf16 v[194:197], v[238:241], v[128:131], 0
	s_waitcnt lgkmcnt(9)
	v_mfma_f32_16x16x32_bf16 v[128:131], v[246:249], v[128:131], 0
	v_mfma_f32_16x16x32_bf16 v[84:87], v[190:193], v[174:177], v[84:87]
	v_mfma_f32_16x16x32_bf16 v[92:95], v[202:205], v[174:177], v[92:95]
	v_mfma_f32_16x16x32_bf16 v[190:193], v[242:245], v[174:177], v[194:197]
	s_waitcnt lgkmcnt(8)
	v_mfma_f32_16x16x32_bf16 v[128:131], v[250:253], v[174:177], v[128:131]
	ds_read_b128 v[174:177], v119 offset:55296
	ds_read_b128 v[194:197], v119 offset:55360
	ds_read_b128 v[202:205], v119 offset:57856
	ds_read_b128 v[234:237], v119 offset:57920
	ds_read_b128 v[238:241], v119 offset:60416
	ds_read_b128 v[242:245], v119 offset:60480
	ds_read_b128 v[246:249], v119 offset:62976
	ds_read_b128 v[250:253], v119 offset:63040
	v_cvt_pk_bf16_f32 v104, v84, v85
	v_cvt_pk_bf16_f32 v105, v86, v87
	v_cvt_pk_bf16_f32 v106, v92, v93
	v_cvt_pk_bf16_f32 v107, v94, v95
	v_cvt_pk_bf16_f32 v94, v128, v129
	v_cvt_pk_bf16_f32 v95, v130, v131
	s_waitcnt lgkmcnt(14)
	v_mfma_f32_16x16x32_bf16 v[84:87], v[182:185], v[104:107], v[88:91]
	v_cvt_pk_bf16_f32 v92, v190, v191
	v_cvt_pk_bf16_f32 v93, v192, v193
	v_pk_mul_f32 v[54:55], v[54:55], v[118:119] op_sel_hi:[1,0]
	s_waitcnt lgkmcnt(13)
	v_mfma_f32_16x16x32_bf16 v[88:91], v[210:213], v[104:107], v[178:181]
	v_mul_f32_e64 v52, v52, v118
	v_mul_f32_e64 v53, v53, v118
	v_pk_mul_f32 v[50:51], v[50:51], v[118:119] op_sel_hi:[1,0]
	v_pk_mul_f32 v[48:49], v[48:49], v[118:119] op_sel_hi:[1,0]
	s_waitcnt lgkmcnt(11)
	v_mfma_f32_16x16x32_bf16 v[128:131], v[218:221], v[104:107], v[186:189]
	v_mul_f32_e64 v46, v46, v118
	v_mul_f32_e64 v47, v47, v118
	v_pk_mul_f32 v[44:45], v[44:45], v[118:119] op_sel_hi:[1,0]
	v_pk_mul_f32 v[42:43], v[42:43], v[118:119] op_sel_hi:[1,0]
	v_mfma_f32_16x16x32_bf16 v[178:181], v[206:209], v[92:95], v[84:87]
	v_mul_f32_e64 v40, v40, v118
	v_mul_f32_e64 v41, v41, v118
	v_pk_mul_f32 v[62:63], v[62:63], v[118:119] op_sel_hi:[1,0]
	v_pk_mul_f32 v[60:61], v[60:61], v[118:119] op_sel_hi:[1,0]
	v_mfma_f32_16x16x32_bf16 v[88:91], v[214:217], v[92:95], v[88:91]
	v_mul_f32_e64 v58, v58, v118
	v_mul_f32_e64 v59, v59, v118
	v_pk_mul_f32 v[56:57], v[56:57], v[118:119] op_sel_hi:[1,0]
	v_pk_mul_f32 v[66:67], v[66:67], v[118:119] op_sel_hi:[1,0]
	s_waitcnt lgkmcnt(10)
	v_mfma_f32_16x16x32_bf16 v[84:87], v[222:225], v[92:95], v[128:131]
	s_nop 2
	ds_read_b128 v[128:131], v135
	ds_read_b128 v[182:185], v152
	ds_read_b128 v[186:189], v153
	ds_read_b128 v[190:193], v154
	ds_read_b128 v[206:209], v155
	ds_read_b128 v[210:213], v156
	ds_read_b128 v[214:217], v157
	ds_read_b128 v[218:221], v158
	v_pk_mul_f32 v[64:65], v[64:65], v[118:119] op_sel_hi:[1,0]
	v_pk_mul_f32 v[70:71], v[70:71], v[118:119] op_sel_hi:[1,0]
	s_waitcnt lgkmcnt(14)
	v_mfma_f32_16x16x32_bf16 v[80:83], v[226:229], v[104:107], v[80:83]
	v_mul_f32_e64 v68, v68, v118
	v_mul_f32_e64 v69, v69, v118
	v_mfma_f32_16x16x32_bf16 v[80:83], v[230:233], v[92:95], v[80:83]
	v_mfma_f32_16x16x32_bf16 v[52:55], v[174:177], v[104:107], v[52:55]
	s_waitcnt lgkmcnt(13)
	v_mfma_f32_16x16x32_bf16 v[48:51], v[202:205], v[104:107], v[48:51]
	s_waitcnt lgkmcnt(11)
	v_mfma_f32_16x16x32_bf16 v[44:47], v[238:241], v[104:107], v[44:47]
	s_waitcnt lgkmcnt(9)
	v_mfma_f32_16x16x32_bf16 v[40:43], v[246:249], v[104:107], v[40:43]
	v_mfma_f32_16x16x32_bf16 v[52:55], v[194:197], v[92:95], v[52:55]
	v_mfma_f32_16x16x32_bf16 v[48:51], v[234:237], v[92:95], v[48:51]
	v_mfma_f32_16x16x32_bf16 v[44:47], v[242:245], v[92:95], v[44:47]
	s_waitcnt lgkmcnt(8)
	v_mfma_f32_16x16x32_bf16 v[40:43], v[250:253], v[92:95], v[40:43]
	s_waitcnt lgkmcnt(7)
	v_mfma_f32_16x16x32_bf16 v[60:63], v[128:131], v[104:107], v[60:63]
	s_waitcnt lgkmcnt(5)
	v_mfma_f32_16x16x32_bf16 v[56:59], v[186:189], v[104:107], v[56:59]
	s_waitcnt lgkmcnt(3)
	v_mfma_f32_16x16x32_bf16 v[64:67], v[206:209], v[104:107], v[64:67]
	s_waitcnt lgkmcnt(1)
	v_mfma_f32_16x16x32_bf16 v[68:71], v[214:217], v[104:107], v[68:71]
	v_mfma_f32_16x16x32_bf16 v[60:63], v[182:185], v[92:95], v[60:63]
	v_mfma_f32_16x16x32_bf16 v[56:59], v[190:193], v[92:95], v[56:59]
	v_mfma_f32_16x16x32_bf16 v[64:67], v[210:213], v[92:95], v[64:67]
	s_waitcnt lgkmcnt(0)
	v_mfma_f32_16x16x32_bf16 v[68:71], v[218:221], v[92:95], v[68:71]
	v_mul_f32_e32 v106, v168, v179
	v_pk_mul_f32 v[104:105], v[180:181], v[180:181]
	v_pk_mul_f32 v[92:93], v[178:179], v[178:179]
	v_cvt_pk_bf16_f32 v106, v106, s0
	v_mul_f32_e32 v94, v168, v178
	v_mov_b32_dpp v92, v92 quad_perm:[1,0,3,2] row_mask:0xf bank_mask:0xf bound_ctrl:1
	v_mov_b32_dpp v93, v93 quad_perm:[1,0,3,2] row_mask:0xf bank_mask:0xf bound_ctrl:1
	ds_write_b16 v171, v106 offset:288
	v_mov_b32_dpp v104, v104 quad_perm:[1,0,3,2] row_mask:0xf bank_mask:0xf bound_ctrl:1
	v_mul_f32_e32 v106, v168, v180
	v_mov_b32_dpp v105, v105 quad_perm:[1,0,3,2] row_mask:0xf bank_mask:0xf bound_ctrl:1
	v_cvt_pk_bf16_f32 v94, v94, s0
	v_pk_fma_f32 v[92:93], v[178:179], v[178:179], v[92:93]
	v_cvt_pk_bf16_f32 v106, v106, s0
	v_pk_fma_f32 v[104:105], v[180:181], v[180:181], v[104:105]
	ds_write_b16 v171, v94
	v_mov_b32_dpp v94, v92 quad_perm:[2,3,0,1] row_mask:0xf bank_mask:0xf bound_ctrl:1
	v_mov_b32_dpp v95, v93 quad_perm:[2,3,0,1] row_mask:0xf bank_mask:0xf bound_ctrl:1
	ds_write_b16 v171, v106 offset:576
	v_mov_b32_dpp v106, v104 quad_perm:[2,3,0,1] row_mask:0xf bank_mask:0xf bound_ctrl:1
	v_mov_b32_dpp v107, v105 quad_perm:[2,3,0,1] row_mask:0xf bank_mask:0xf bound_ctrl:1
	v_pk_add_f32 v[92:93], v[92:93], v[94:95]
	v_pk_add_f32 v[104:105], v[104:105], v[106:107]
	s_nop 0
	v_mov_b32_dpp v94, v92 row_half_mirror row_mask:0xf bank_mask:0xf bound_ctrl:1
	v_mov_b32_dpp v95, v93 row_half_mirror row_mask:0xf bank_mask:0xf bound_ctrl:1
	v_mov_b32_dpp v106, v104 row_half_mirror row_mask:0xf bank_mask:0xf bound_ctrl:1
	v_mov_b32_dpp v107, v105 row_half_mirror row_mask:0xf bank_mask:0xf bound_ctrl:1
	v_pk_add_f32 v[92:93], v[92:93], v[94:95]
	v_pk_add_f32 v[128:129], v[104:105], v[106:107]
	v_mul_f32_e32 v104, v168, v181
	v_mov_b32_dpp v94, v92 row_mirror row_mask:0xf bank_mask:0xf bound_ctrl:1
	v_mov_b32_dpp v95, v93 row_mirror row_mask:0xf bank_mask:0xf bound_ctrl:1
	v_mov_b32_dpp v130, v128 row_mirror row_mask:0xf bank_mask:0xf bound_ctrl:1
	v_mov_b32_dpp v131, v129 row_mirror row_mask:0xf bank_mask:0xf bound_ctrl:1
	v_cvt_pk_bf16_f32 v104, v104, s0
	ds_write_b16 v171, v104 offset:864
	s_and_saveexec_b64 s[10:11], s[4:5]
	v_pk_add_f32 v[106:107], v[128:129], v[130:131]
	v_pk_add_f32 v[104:105], v[92:93], v[94:95]
	ds_write_b128 v169, v[104:107]
	s_or_b64 exec, exec, s[10:11]
	v_pk_mul_f32 v[92:93], v[88:89], v[88:89]
	v_mul_f32_e32 v94, v168, v88
	v_pk_mul_f32 v[104:105], v[90:91], v[90:91]
	v_mov_b32_dpp v92, v92 quad_perm:[1,0,3,2] row_mask:0xf bank_mask:0xf bound_ctrl:1
	v_mov_b32_dpp v93, v93 quad_perm:[1,0,3,2] row_mask:0xf bank_mask:0xf bound_ctrl:1
	v_pk_fma_f32 v[92:93], v[88:89], v[88:89], v[92:93]
	v_mul_f32_e32 v88, v168, v89
	v_mul_f32_e32 v89, v168, v90
	v_cvt_pk_bf16_f32 v88, v88, s0
	v_cvt_pk_bf16_f32 v89, v89, s0
	ds_write_b16 v171, v88 offset:4896
	v_mov_b32_dpp v88, v104 quad_perm:[1,0,3,2] row_mask:0xf bank_mask:0xf bound_ctrl:1
	ds_write_b16 v171, v89 offset:5184
	v_mov_b32_dpp v89, v105 quad_perm:[1,0,3,2] row_mask:0xf bank_mask:0xf bound_ctrl:1
	v_cvt_pk_bf16_f32 v94, v94, s0
	v_pk_fma_f32 v[88:89], v[90:91], v[90:91], v[88:89]
	ds_write_b16 v171, v94 offset:4608
	v_mov_b32_dpp v94, v92 quad_perm:[2,3,0,1] row_mask:0xf bank_mask:0xf bound_ctrl:1
	v_mov_b32_dpp v95, v93 quad_perm:[2,3,0,1] row_mask:0xf bank_mask:0xf bound_ctrl:1
	v_mov_b32_dpp v104, v88 quad_perm:[2,3,0,1] row_mask:0xf bank_mask:0xf bound_ctrl:1
	v_mov_b32_dpp v105, v89 quad_perm:[2,3,0,1] row_mask:0xf bank_mask:0xf bound_ctrl:1
	v_pk_add_f32 v[92:93], v[92:93], v[94:95]
	v_pk_add_f32 v[88:89], v[88:89], v[104:105]
	v_mul_f32_e32 v90, v168, v91
	v_mov_b32_dpp v94, v92 row_half_mirror row_mask:0xf bank_mask:0xf bound_ctrl:1
	v_mov_b32_dpp v95, v93 row_half_mirror row_mask:0xf bank_mask:0xf bound_ctrl:1
	v_mov_b32_dpp v104, v88 row_half_mirror row_mask:0xf bank_mask:0xf bound_ctrl:1
	v_mov_b32_dpp v105, v89 row_half_mirror row_mask:0xf bank_mask:0xf bound_ctrl:1
	v_pk_add_f32 v[92:93], v[92:93], v[94:95]
	v_pk_add_f32 v[88:89], v[88:89], v[104:105]
	v_cvt_pk_bf16_f32 v90, v90, s0
	v_mov_b32_dpp v94, v92 row_mirror row_mask:0xf bank_mask:0xf bound_ctrl:1
	v_mov_b32_dpp v95, v93 row_mirror row_mask:0xf bank_mask:0xf bound_ctrl:1
	v_mov_b32_dpp v128, v88 row_mirror row_mask:0xf bank_mask:0xf bound_ctrl:1
	v_mov_b32_dpp v129, v89 row_mirror row_mask:0xf bank_mask:0xf bound_ctrl:1
	ds_write_b16 v171, v90 offset:5472
	s_and_saveexec_b64 s[10:11], s[4:5]
	v_pk_add_f32 v[90:91], v[88:89], v[128:129]
	v_pk_add_f32 v[88:89], v[92:93], v[94:95]
	ds_write_b128 v169, v[88:91] offset:64
	s_or_b64 exec, exec, s[10:11]
	v_pk_mul_f32 v[88:89], v[84:85], v[84:85]
	v_mul_f32_e32 v90, v168, v84
	v_pk_mul_f32 v[92:93], v[86:87], v[86:87]
	v_mov_b32_dpp v88, v88 quad_perm:[1,0,3,2] row_mask:0xf bank_mask:0xf bound_ctrl:1
	v_mov_b32_dpp v89, v89 quad_perm:[1,0,3,2] row_mask:0xf bank_mask:0xf bound_ctrl:1
	v_pk_fma_f32 v[88:89], v[84:85], v[84:85], v[88:89]
	v_mul_f32_e32 v84, v168, v85
	v_mul_f32_e32 v85, v168, v86
	v_cvt_pk_bf16_f32 v84, v84, s0
	v_cvt_pk_bf16_f32 v85, v85, s0
	ds_write_b16 v171, v84 offset:9504
	v_mov_b32_dpp v84, v92 quad_perm:[1,0,3,2] row_mask:0xf bank_mask:0xf bound_ctrl:1
	ds_write_b16 v171, v85 offset:9792
	v_mov_b32_dpp v85, v93 quad_perm:[1,0,3,2] row_mask:0xf bank_mask:0xf bound_ctrl:1
	v_cvt_pk_bf16_f32 v90, v90, s0
	v_pk_fma_f32 v[84:85], v[86:87], v[86:87], v[84:85]
	ds_write_b16 v171, v90 offset:9216
	v_mov_b32_dpp v90, v88 quad_perm:[2,3,0,1] row_mask:0xf bank_mask:0xf bound_ctrl:1
	v_mov_b32_dpp v91, v89 quad_perm:[2,3,0,1] row_mask:0xf bank_mask:0xf bound_ctrl:1
	v_mov_b32_dpp v92, v84 quad_perm:[2,3,0,1] row_mask:0xf bank_mask:0xf bound_ctrl:1
	v_mov_b32_dpp v93, v85 quad_perm:[2,3,0,1] row_mask:0xf bank_mask:0xf bound_ctrl:1
	v_pk_add_f32 v[88:89], v[88:89], v[90:91]
	v_pk_add_f32 v[84:85], v[84:85], v[92:93]
	v_mul_f32_e32 v86, v168, v87
	v_mov_b32_dpp v90, v88 row_half_mirror row_mask:0xf bank_mask:0xf bound_ctrl:1
	v_mov_b32_dpp v91, v89 row_half_mirror row_mask:0xf bank_mask:0xf bound_ctrl:1
	v_mov_b32_dpp v92, v84 row_half_mirror row_mask:0xf bank_mask:0xf bound_ctrl:1
	v_mov_b32_dpp v93, v85 row_half_mirror row_mask:0xf bank_mask:0xf bound_ctrl:1
	v_pk_add_f32 v[88:89], v[88:89], v[90:91]
	v_pk_add_f32 v[84:85], v[84:85], v[92:93]
	v_cvt_pk_bf16_f32 v86, v86, s0
	v_mov_b32_dpp v90, v88 row_mirror row_mask:0xf bank_mask:0xf bound_ctrl:1
	v_mov_b32_dpp v91, v89 row_mirror row_mask:0xf bank_mask:0xf bound_ctrl:1
	v_mov_b32_dpp v92, v84 row_mirror row_mask:0xf bank_mask:0xf bound_ctrl:1
	v_mov_b32_dpp v93, v85 row_mirror row_mask:0xf bank_mask:0xf bound_ctrl:1
	ds_write_b16 v171, v86 offset:10080
	s_and_saveexec_b64 s[10:11], s[4:5]
	v_pk_add_f32 v[86:87], v[84:85], v[92:93]
	v_pk_add_f32 v[84:85], v[88:89], v[90:91]
	ds_write_b128 v169, v[84:87] offset:128
	s_or_b64 exec, exec, s[10:11]
	v_pk_mul_f32 v[84:85], v[80:81], v[80:81]
	v_mul_f32_e32 v86, v168, v80
	v_pk_mul_f32 v[88:89], v[82:83], v[82:83]
	v_mov_b32_dpp v84, v84 quad_perm:[1,0,3,2] row_mask:0xf bank_mask:0xf bound_ctrl:1
	v_mov_b32_dpp v85, v85 quad_perm:[1,0,3,2] row_mask:0xf bank_mask:0xf bound_ctrl:1
	v_pk_fma_f32 v[84:85], v[80:81], v[80:81], v[84:85]
	v_mul_f32_e32 v80, v168, v81
	v_mul_f32_e32 v81, v168, v82
	v_cvt_pk_bf16_f32 v80, v80, s0
	v_cvt_pk_bf16_f32 v81, v81, s0
	ds_write_b16 v171, v80 offset:14112
	v_mov_b32_dpp v80, v88 quad_perm:[1,0,3,2] row_mask:0xf bank_mask:0xf bound_ctrl:1
	ds_write_b16 v171, v81 offset:14400
	v_mov_b32_dpp v81, v89 quad_perm:[1,0,3,2] row_mask:0xf bank_mask:0xf bound_ctrl:1
	v_cvt_pk_bf16_f32 v86, v86, s0
	v_pk_fma_f32 v[80:81], v[82:83], v[82:83], v[80:81]
	ds_write_b16 v171, v86 offset:13824
	v_mov_b32_dpp v86, v84 quad_perm:[2,3,0,1] row_mask:0xf bank_mask:0xf bound_ctrl:1
	v_mov_b32_dpp v87, v85 quad_perm:[2,3,0,1] row_mask:0xf bank_mask:0xf bound_ctrl:1
	v_mov_b32_dpp v88, v80 quad_perm:[2,3,0,1] row_mask:0xf bank_mask:0xf bound_ctrl:1
	v_mov_b32_dpp v89, v81 quad_perm:[2,3,0,1] row_mask:0xf bank_mask:0xf bound_ctrl:1
	v_pk_add_f32 v[84:85], v[84:85], v[86:87]
	v_pk_add_f32 v[80:81], v[80:81], v[88:89]
	v_mul_f32_e32 v82, v168, v83
	v_mov_b32_dpp v86, v84 row_half_mirror row_mask:0xf bank_mask:0xf bound_ctrl:1
	v_mov_b32_dpp v87, v85 row_half_mirror row_mask:0xf bank_mask:0xf bound_ctrl:1
	v_mov_b32_dpp v88, v80 row_half_mirror row_mask:0xf bank_mask:0xf bound_ctrl:1
	v_mov_b32_dpp v89, v81 row_half_mirror row_mask:0xf bank_mask:0xf bound_ctrl:1
	v_pk_add_f32 v[84:85], v[84:85], v[86:87]
	v_pk_add_f32 v[80:81], v[80:81], v[88:89]
	v_cvt_pk_bf16_f32 v82, v82, s0
	v_mov_b32_dpp v86, v84 row_mirror row_mask:0xf bank_mask:0xf bound_ctrl:1
	v_mov_b32_dpp v87, v85 row_mirror row_mask:0xf bank_mask:0xf bound_ctrl:1
	v_mov_b32_dpp v88, v80 row_mirror row_mask:0xf bank_mask:0xf bound_ctrl:1
	v_mov_b32_dpp v89, v81 row_mirror row_mask:0xf bank_mask:0xf bound_ctrl:1
	ds_write_b16 v171, v82 offset:14688
	s_and_saveexec_b64 s[10:11], s[4:5]
	v_pk_add_f32 v[82:83], v[80:81], v[88:89]
	v_pk_add_f32 v[80:81], v[84:85], v[86:87]
	ds_write_b128 v169, v[80:83] offset:192
	s_or_b64 exec, exec, s[10:11]
	s_andn2_b64 vcc, exec, s[8:9]
	s_waitcnt lgkmcnt(0)
	s_barrier
	ds_read2st64_b32 v[174:175], v137 offset1:1
	ds_read2st64_b32 v[176:177], v137 offset0:2 offset1:3
	ds_read2st64_b32 v[178:179], v137 offset0:4 offset1:5
	ds_read2st64_b32 v[180:181], v137 offset0:6 offset1:7
	ds_read_b128 v[84:87], v163
	ds_read_b128 v[80:83], v163 offset:16
	s_cbranch_vccnz .Lscan_last
	s_waitcnt vmcnt(2)
	v_mov_b32_e32 v118, v172
	ds_write_b128 v164, v[0:3]
	ds_write_b128 v164, v[4:7] offset:16
	ds_write_b128 v164, v[8:11] offset:18432
	ds_write_b128 v164, v[12:15] offset:18448
	ds_write_b128 v164, v[16:19] offset:36864
	ds_write_b128 v164, v[20:23] offset:36880
	ds_write_b128 v165, v[32:35] offset:55296
	ds_write_b128 v165, v[36:39] offset:55312
	ds_write_b128 v166, v[24:27]
	ds_write_b128 v167, v[28:31]
	s_branch .LBB0_708
.Lscan_last:
	s_waitcnt lgkmcnt(0)
	s_branch .LBB0_708
